# GU GEMM K-loop: LDS-DMA group issued before the fragment ds_reads in every load segment (longer prefetch lead)
# speedup vs baseline: 1.0015x; 1.0015x over previous
; #define PG8_STAGE(bufoff, gbase, voff) do { const char* _gb = (const char*)(gbase); asm volatile("" : "+s"(_gb)); _Pragma("unroll") for (int _i = 0; _i < 2; ++_i) { \
;         unsigned _vo = (voff)[_i]; asm volatile("" : "+v"(_vo));     \
;         __builtin_amdgcn_global_load_lds((const unsigned*)(_gb + _vo), (LAS unsigned*)(lds + (bufoff) + ldsw + _i * 8192), 16, 0, 0); } } while (0)
; #define PG8_LDA(dst, b, h) do { _Pragma("unroll") for (int m = 0; m < 4; ++m) _Pragma("unroll") for (int k = 0; k < 2; ++k) dst[m][k] = *(const LAS bf16x8*)(lds + PG8_SA(b, h) + aoff + m * 2048 + k * 1024); } while (0)
; #define PG8_LDB(dst, b, h) do { _Pragma("unroll") for (int n = 0; n < 2; ++n) _Pragma("unroll") for (int k = 0; k < 2; ++k) dst[n][k] = *(const LAS bf16x8*)(lds + PG8_SB(b, h) + boff + n * 2048 + k * 1024); } while (0)
; #define PG8_MMA(ai, bj, At, Bt) do { __builtin_amdgcn_s_setprio(1); _Pragma("unroll") for (int m = 0; m < 4; ++m) _Pragma("unroll") for (int n = 0; n < 2; ++n) _Pragma("unroll") for (int k = 0; k < 2; ++k) \
;         acc[ai][bj][m][n] = __builtin_amdgcn_mfma_f32_16x16x32_bf16(Bt[n][k], At[m][k], acc[ai][bj][m][n], 0, 0, 0); __builtin_amdgcn_s_setprio(0); } while (0)
; #define PG8_WAIT_V(n) asm volatile("s_waitcnt vmcnt(" #n ")" ::: "memory")
; #define PG8_WAIT_L(n) asm volatile("s_waitcnt lgkmcnt(" #n ")" ::: "memory")
; #define PG8_BAR __builtin_amdgcn_s_barrier()
; #define PG8_SCHED __builtin_amdgcn_sched_barrier(0)
; template <class Epi, class Sched>
; DI void gemm_phase(int wv, LAS unsigned char* lds, const Gemm g, const Sched& S, const Epi& E) {
;     ...
;         for (int t = 0; t < nt; t += 2) {
;             const bool last = (t == nt - 2);
;             const char* a1 = cA + (size_t)(t + 1) * kstep;
;             const char* a2 = last ? nA : cA + (size_t)(t + 2) * kstep; const char* b2 = last ? nB : cB + (size_t)(t + 2) * kstep;
;             const char* a3 = a2 + kstep; const char* b3 = b2 + kstep;
;             PG8_LDB(B0, 0, 0); PG8_LDB(B1, 0, 1); PG8_SCHED; PG8_LDA(At, 0, 0); PG8_STAGE(PG8_SA(1, 1), a1 + hstepA, voffA);
;             PG8_WAIT_V(8); PG8_WAIT_L(0); PG8_BAR; PG8_MMA(0, 0, At, B0); PG8_MMA(0, 1, At, B1); PG8_BAR; PG8_SCHED;
;             PG8_LDA(At, 0, 1); PG8_STAGE(PG8_SB(0, 0), b2, voffB); PG8_STAGE(PG8_SB(0, 1), b2 + hstepB, voffB); PG8_STAGE(PG8_SA(0, 0), a2, voffA);
.LBB0_1816:
	s_ashr_i32 s15, s14, 31
	s_lshl_b64 s[18:19], s[14:15], 19
	s_add_u32 s18, s34, s18
	s_addc_u32 s19, s35, s19
	s_and_b64 s[20:21], s[24:25], exec
	s_cselect_b32 s1, s19, s3
	s_cselect_b32 s23, s18, s2
	s_ashr_i32 s17, s16, 31
	s_lshl_b64 s[20:21], s[16:17], 19
	s_add_u32 s20, s36, s20
	s_addc_u32 s21, s37, s21
	s_and_b64 s[28:29], s[24:25], exec
	s_cselect_b32 s17, s21, s27
	s_cselect_b32 s55, s20, s26
	s_add_u32 s56, s26, 0x100
	s_addc_u32 s57, s27, 0
	s_add_u32 s2, s2, 0x40080
	s_addc_u32 s3, s3, 0
	s_mov_b32 s60, -2
	s_add_u32 s26, s2, 0xfffc0080
	s_addc_u32 s27, s3, -1
	s_cmp_eq_u32 s60, 12
	s_cselect_b32 s30, s23, s26
	s_cselect_b32 s31, s1, s27
	s_cselect_b32 s28, s55, s56
	s_cselect_b32 s29, s17, s57
	s_add_u32 s26, s30, 0x80
	s_addc_u32 s27, s31, 0
	s_add_i32 s61, 0, 0x10000
	s_add_i32 s66, 0, 0x14000
	s_mov_b64 s[64:65], s[2:3]
	v_mov_b32_e32 v177, v170
	s_add_i32 m0, s46, 0xc000
	s_nop 0
	global_load_lds_dwordx4 v177, s[64:65]
	v_mov_b32_e32 v177, v172
	s_add_i32 m0, s46, 0xe000
	s_nop 0
	global_load_lds_dwordx4 v177, s[64:65]
	v_add_u32_e32 v142, s61, v0
	v_add_u32_e32 v158, s66, v0
	ds_read_b128 v[98:101], v142
	ds_read_b128 v[118:121], v142 offset:1024
	ds_read_b128 v[138:141], v142 offset:2048
	ds_read_b128 v[142:145], v142 offset:3072
	ds_read_b128 v[146:149], v158
	ds_read_b128 v[150:153], v158 offset:1024
	ds_read_b128 v[154:157], v158 offset:2048
	ds_read_b128 v[158:161], v158 offset:3072
	ds_read_b128 v[162:165], v176
	ds_read_b128 v[166:169], v176 offset:1024
	ds_read_b128 v[178:181], v176 offset:2048
	ds_read_b128 v[182:185], v176 offset:3072
	ds_read_b128 v[186:189], v176 offset:4096
	ds_read_b128 v[190:193], v176 offset:5120
	ds_read_b128 v[194:197], v176 offset:6144
	ds_read_b128 v[198:201], v176 offset:7168
	s_waitcnt vmcnt(8)
	s_waitcnt lgkmcnt(0)
	s_barrier
	s_setprio 1
	s_waitcnt lgkmcnt(0)
	v_mfma_f32_16x16x32_bf16 v[134:137], v[98:101], v[162:165], 0
	v_mfma_f32_16x16x32_bf16 v[130:133], v[138:141], v[162:165], 0
	v_mfma_f32_16x16x32_bf16 v[114:117], v[98:101], v[178:181], 0
	v_mfma_f32_16x16x32_bf16 v[110:113], v[138:141], v[178:181], 0
	v_mfma_f32_16x16x32_bf16 v[94:97], v[98:101], v[186:189], 0
	v_mfma_f32_16x16x32_bf16 v[90:93], v[138:141], v[186:189], 0
	v_mfma_f32_16x16x32_bf16 v[78:81], v[98:101], v[194:197], 0
	v_mfma_f32_16x16x32_bf16 v[74:77], v[138:141], v[194:197], 0
	v_mfma_f32_16x16x32_bf16 v[134:137], v[118:121], v[166:169], v[134:137]
	v_mfma_f32_16x16x32_bf16 v[130:133], v[142:145], v[166:169], v[130:133]
	v_mfma_f32_16x16x32_bf16 v[114:117], v[118:121], v[182:185], v[114:117]
	v_mfma_f32_16x16x32_bf16 v[110:113], v[142:145], v[182:185], v[110:113]
	v_mfma_f32_16x16x32_bf16 v[94:97], v[118:121], v[190:193], v[94:97]
	v_mfma_f32_16x16x32_bf16 v[90:93], v[142:145], v[190:193], v[90:93]
	v_mfma_f32_16x16x32_bf16 v[78:81], v[118:121], v[198:201], v[78:81]
	v_mfma_f32_16x16x32_bf16 v[74:77], v[142:145], v[198:201], v[74:77]
	s_setprio 0
	s_setprio 1
	v_mfma_f32_16x16x32_bf16 v[126:129], v[146:149], v[162:165], 0
	v_mfma_f32_16x16x32_bf16 v[122:125], v[154:157], v[162:165], 0
	v_mfma_f32_16x16x32_bf16 v[106:109], v[146:149], v[178:181], 0
	v_mfma_f32_16x16x32_bf16 v[102:105], v[154:157], v[178:181], 0
	v_mfma_f32_16x16x32_bf16 v[86:89], v[146:149], v[186:189], 0
	v_mfma_f32_16x16x32_bf16 v[82:85], v[154:157], v[186:189], 0
	v_mfma_f32_16x16x32_bf16 v[70:73], v[146:149], v[194:197], 0
	v_mfma_f32_16x16x32_bf16 v[66:69], v[154:157], v[194:197], 0
	v_mfma_f32_16x16x32_bf16 v[126:129], v[150:153], v[166:169], v[126:129]
	v_mfma_f32_16x16x32_bf16 v[122:125], v[158:161], v[166:169], v[122:125]
	v_mfma_f32_16x16x32_bf16 v[106:109], v[150:153], v[182:185], v[106:109]
	v_mfma_f32_16x16x32_bf16 v[102:105], v[158:161], v[182:185], v[102:105]
	v_mfma_f32_16x16x32_bf16 v[86:89], v[150:153], v[190:193], v[86:89]
	v_mfma_f32_16x16x32_bf16 v[82:85], v[158:161], v[190:193], v[82:85]
	v_mfma_f32_16x16x32_bf16 v[70:73], v[150:153], v[198:201], v[70:73]
	v_mfma_f32_16x16x32_bf16 v[66:69], v[158:161], v[198:201], v[66:69]
	s_setprio 0
	s_barrier
	s_mov_b64 s[64:65], s[28:29]
	v_mov_b32_e32 v177, v171
	s_add_i32 s61, s61, s38
	s_mov_b32 m0, s61
	s_nop 0
	global_load_lds_dwordx4 v177, s[64:65]
	v_mov_b32_e32 v177, v173
	s_add_i32 m0, s61, 0x2000
	s_nop 0
	global_load_lds_dwordx4 v177, s[64:65]
	s_add_u32 s64, s28, 0x40000
	s_addc_u32 s65, s29, 0
	v_mov_b32_e32 v177, v171
	s_add_i32 s61, s66, s38
	s_mov_b32 m0, s61
	s_nop 0
	global_load_lds_dwordx4 v177, s[64:65]
	v_mov_b32_e32 v177, v173
	s_add_i32 m0, s61, 0x2000
	s_nop 0
	global_load_lds_dwordx4 v177, s[64:65]
	s_mov_b64 s[64:65], s[30:31]
	v_mov_b32_e32 v177, v170
	s_mov_b32 m0, s46
	s_nop 0
	global_load_lds_dwordx4 v177, s[64:65]
	v_mov_b32_e32 v177, v172
	s_mov_b32 m0, s47
	s_nop 0
	global_load_lds_dwordx4 v177, s[64:65]
	ds_read_b128 v[162:165], v176 offset:16384
	ds_read_b128 v[166:169], v176 offset:17408
	ds_read_b128 v[178:181], v176 offset:18432
	ds_read_b128 v[182:185], v176 offset:19456
	ds_read_b128 v[186:189], v176 offset:20480
	ds_read_b128 v[190:193], v176 offset:21504
	ds_read_b128 v[194:197], v176 offset:22528
	ds_read_b128 v[198:201], v176 offset:23552
	s_waitcnt vmcnt(8)
	s_waitcnt lgkmcnt(0)
	s_barrier
; #define PG8_STAGE(bufoff, gbase, voff) do { const char* _gb = (const char*)(gbase); asm volatile("" : "+s"(_gb)); _Pragma("unroll") for (int _i = 0; _i < 2; ++_i) { \
;         unsigned _vo = (voff)[_i]; asm volatile("" : "+v"(_vo));     \
;         __builtin_amdgcn_global_load_lds((const unsigned*)(_gb + _vo), (LAS unsigned*)(lds + (bufoff) + ldsw + _i * 8192), 16, 0, 0); } } while (0)
; #define PG8_LDA(dst, b, h) do { _Pragma("unroll") for (int m = 0; m < 4; ++m) _Pragma("unroll") for (int k = 0; k < 2; ++k) dst[m][k] = *(const LAS bf16x8*)(lds + PG8_SA(b, h) + aoff + m * 2048 + k * 1024); } while (0)
; #define PG8_LDB(dst, b, h) do { _Pragma("unroll") for (int n = 0; n < 2; ++n) _Pragma("unroll") for (int k = 0; k < 2; ++k) dst[n][k] = *(const LAS bf16x8*)(lds + PG8_SB(b, h) + boff + n * 2048 + k * 1024); } while (0)
; #define PG8_MMA(ai, bj, At, Bt) do { __builtin_amdgcn_s_setprio(1); _Pragma("unroll") for (int m = 0; m < 4; ++m) _Pragma("unroll") for (int n = 0; n < 2; ++n) _Pragma("unroll") for (int k = 0; k < 2; ++k) \
;         acc[ai][bj][m][n] = __builtin_amdgcn_mfma_f32_16x16x32_bf16(Bt[n][k], At[m][k], acc[ai][bj][m][n], 0, 0, 0); __builtin_amdgcn_s_setprio(0); } while (0)
; #define PG8_WAIT_V(n) asm volatile("s_waitcnt vmcnt(" #n ")" ::: "memory")
; #define PG8_WAIT_L(n) asm volatile("s_waitcnt lgkmcnt(" #n ")" ::: "memory")
; #define PG8_BAR __builtin_amdgcn_s_barrier()
; #define PG8_SCHED __builtin_amdgcn_sched_barrier(0)
; template <class Epi, class Sched>
; DI void gemm_phase(int wv, LAS unsigned char* lds, const Gemm g, const Sched& S, const Epi& E) {
;     ...
;             PG8_WAIT_V(8); PG8_WAIT_L(0); PG8_BAR; PG8_MMA(1, 0, At, B0); PG8_MMA(1, 1, At, B1); PG8_BAR; PG8_SCHED;
;             PG8_LDB(B0, 1, 0); PG8_LDB(B1, 1, 1); PG8_SCHED; PG8_LDA(At, 1, 0); PG8_STAGE(PG8_SA(0, 1), a2 + hstepA, voffA);
;             PG8_WAIT_V(8); PG8_WAIT_L(0); PG8_BAR; PG8_MMA(0, 0, At, B0); PG8_MMA(0, 1, At, B1); PG8_BAR; PG8_SCHED;
	s_setprio 1
	s_waitcnt lgkmcnt(0)
	v_mfma_f32_16x16x32_bf16 v[62:65], v[98:101], v[162:165], 0
	v_mfma_f32_16x16x32_bf16 v[58:61], v[138:141], v[162:165], 0
	v_mfma_f32_16x16x32_bf16 v[46:49], v[98:101], v[178:181], 0
	v_mfma_f32_16x16x32_bf16 v[42:45], v[138:141], v[178:181], 0
	v_mfma_f32_16x16x32_bf16 v[30:33], v[98:101], v[186:189], 0
	v_mfma_f32_16x16x32_bf16 v[26:29], v[138:141], v[186:189], 0
	v_mfma_f32_16x16x32_bf16 v[14:17], v[98:101], v[194:197], 0
	v_mfma_f32_16x16x32_bf16 v[10:13], v[138:141], v[194:197], 0
	v_mfma_f32_16x16x32_bf16 v[62:65], v[118:121], v[166:169], v[62:65]
	v_mfma_f32_16x16x32_bf16 v[58:61], v[142:145], v[166:169], v[58:61]
	v_mfma_f32_16x16x32_bf16 v[46:49], v[118:121], v[182:185], v[46:49]
	v_mfma_f32_16x16x32_bf16 v[42:45], v[142:145], v[182:185], v[42:45]
	v_mfma_f32_16x16x32_bf16 v[30:33], v[118:121], v[190:193], v[30:33]
	v_mfma_f32_16x16x32_bf16 v[26:29], v[142:145], v[190:193], v[26:29]
	v_mfma_f32_16x16x32_bf16 v[14:17], v[118:121], v[198:201], v[14:17]
	v_mfma_f32_16x16x32_bf16 v[10:13], v[142:145], v[198:201], v[10:13]
	s_setprio 0
	s_setprio 1
	v_mfma_f32_16x16x32_bf16 v[54:57], v[146:149], v[162:165], 0
	v_mfma_f32_16x16x32_bf16 v[50:53], v[154:157], v[162:165], 0
	v_mfma_f32_16x16x32_bf16 v[38:41], v[146:149], v[178:181], 0
	v_mfma_f32_16x16x32_bf16 v[34:37], v[154:157], v[178:181], 0
	v_mfma_f32_16x16x32_bf16 v[22:25], v[146:149], v[186:189], 0
	v_mfma_f32_16x16x32_bf16 v[18:21], v[154:157], v[186:189], 0
	v_mfma_f32_16x16x32_bf16 v[6:9], v[146:149], v[194:197], 0
	v_mfma_f32_16x16x32_bf16 v[2:5], v[154:157], v[194:197], 0
	v_mfma_f32_16x16x32_bf16 v[54:57], v[150:153], v[166:169], v[54:57]
	v_mfma_f32_16x16x32_bf16 v[50:53], v[158:161], v[166:169], v[50:53]
	v_mfma_f32_16x16x32_bf16 v[38:41], v[150:153], v[182:185], v[38:41]
	v_mfma_f32_16x16x32_bf16 v[34:37], v[158:161], v[182:185], v[34:37]
	v_mfma_f32_16x16x32_bf16 v[22:25], v[150:153], v[190:193], v[22:25]
	v_mfma_f32_16x16x32_bf16 v[18:21], v[158:161], v[190:193], v[18:21]
	v_mfma_f32_16x16x32_bf16 v[6:9], v[150:153], v[198:201], v[6:9]
	v_mfma_f32_16x16x32_bf16 v[2:5], v[158:161], v[198:201], v[2:5]
	s_setprio 0
	s_barrier
	s_add_i32 s61, 0, 0x18000
	s_add_i32 s64, 0, 0x1c000
	s_add_u32 s30, s30, 0x40000
	s_addc_u32 s31, s31, 0
	v_mov_b32_e32 v177, v170
	s_mov_b32 m0, s48
	s_nop 0
	global_load_lds_dwordx4 v177, s[30:31]
	v_mov_b32_e32 v177, v172
	s_mov_b32 m0, s49
	s_nop 0
	global_load_lds_dwordx4 v177, s[30:31]
	v_add_u32_e32 v142, s61, v0
	v_add_u32_e32 v158, s64, v0
	ds_read_b128 v[98:101], v142
	ds_read_b128 v[118:121], v142 offset:1024
	ds_read_b128 v[138:141], v142 offset:2048
	ds_read_b128 v[142:145], v142 offset:3072
	ds_read_b128 v[146:149], v158
	ds_read_b128 v[150:153], v158 offset:1024
	ds_read_b128 v[154:157], v158 offset:2048
	ds_read_b128 v[158:161], v158 offset:3072
	ds_read_b128 v[162:165], v176 offset:32768
	ds_read_b128 v[166:169], v176 offset:33792
	ds_read_b128 v[178:181], v176 offset:34816
	ds_read_b128 v[182:185], v176 offset:35840
	ds_read_b128 v[186:189], v176 offset:36864
	ds_read_b128 v[190:193], v176 offset:37888
	ds_read_b128 v[194:197], v176 offset:38912
	ds_read_b128 v[198:201], v176 offset:39936
	s_waitcnt vmcnt(8)
	s_waitcnt lgkmcnt(0)
	s_barrier
	s_setprio 1
	s_waitcnt lgkmcnt(0)
	v_mfma_f32_16x16x32_bf16 v[134:137], v[98:101], v[162:165], v[134:137]
	v_mfma_f32_16x16x32_bf16 v[130:133], v[138:141], v[162:165], v[130:133]
	v_mfma_f32_16x16x32_bf16 v[114:117], v[98:101], v[178:181], v[114:117]
	v_mfma_f32_16x16x32_bf16 v[110:113], v[138:141], v[178:181], v[110:113]
	v_mfma_f32_16x16x32_bf16 v[94:97], v[98:101], v[186:189], v[94:97]
	v_mfma_f32_16x16x32_bf16 v[90:93], v[138:141], v[186:189], v[90:93]
	v_mfma_f32_16x16x32_bf16 v[78:81], v[98:101], v[194:197], v[78:81]
	v_mfma_f32_16x16x32_bf16 v[74:77], v[138:141], v[194:197], v[74:77]
	v_mfma_f32_16x16x32_bf16 v[134:137], v[118:121], v[166:169], v[134:137]
	v_mfma_f32_16x16x32_bf16 v[130:133], v[142:145], v[166:169], v[130:133]
	v_mfma_f32_16x16x32_bf16 v[114:117], v[118:121], v[182:185], v[114:117]
	v_mfma_f32_16x16x32_bf16 v[110:113], v[142:145], v[182:185], v[110:113]
	v_mfma_f32_16x16x32_bf16 v[94:97], v[118:121], v[190:193], v[94:97]
	v_mfma_f32_16x16x32_bf16 v[90:93], v[142:145], v[190:193], v[90:93]
	v_mfma_f32_16x16x32_bf16 v[78:81], v[118:121], v[198:201], v[78:81]
	v_mfma_f32_16x16x32_bf16 v[74:77], v[142:145], v[198:201], v[74:77]
	s_setprio 0
	s_setprio 1
	v_mfma_f32_16x16x32_bf16 v[126:129], v[146:149], v[162:165], v[126:129]
	v_mfma_f32_16x16x32_bf16 v[122:125], v[154:157], v[162:165], v[122:125]
	v_mfma_f32_16x16x32_bf16 v[106:109], v[146:149], v[178:181], v[106:109]
	v_mfma_f32_16x16x32_bf16 v[102:105], v[154:157], v[178:181], v[102:105]
	v_mfma_f32_16x16x32_bf16 v[86:89], v[146:149], v[186:189], v[86:89]
	v_mfma_f32_16x16x32_bf16 v[82:85], v[154:157], v[186:189], v[82:85]
	v_mfma_f32_16x16x32_bf16 v[70:73], v[146:149], v[194:197], v[70:73]
	v_mfma_f32_16x16x32_bf16 v[66:69], v[154:157], v[194:197], v[66:69]
	v_mfma_f32_16x16x32_bf16 v[126:129], v[150:153], v[166:169], v[126:129]
	v_mfma_f32_16x16x32_bf16 v[122:125], v[158:161], v[166:169], v[122:125]
	v_mfma_f32_16x16x32_bf16 v[106:109], v[150:153], v[182:185], v[106:109]
	v_mfma_f32_16x16x32_bf16 v[102:105], v[158:161], v[182:185], v[102:105]
	v_mfma_f32_16x16x32_bf16 v[86:89], v[150:153], v[190:193], v[86:89]
	v_mfma_f32_16x16x32_bf16 v[82:85], v[158:161], v[190:193], v[82:85]
	v_mfma_f32_16x16x32_bf16 v[70:73], v[150:153], v[198:201], v[70:73]
	v_mfma_f32_16x16x32_bf16 v[66:69], v[158:161], v[198:201], v[66:69]
	s_setprio 0
	s_barrier
; #define PG8_STAGE(bufoff, gbase, voff) do { const char* _gb = (const char*)(gbase); asm volatile("" : "+s"(_gb)); _Pragma("unroll") for (int _i = 0; _i < 2; ++_i) { \
;         unsigned _vo = (voff)[_i]; asm volatile("" : "+v"(_vo));     \
;         __builtin_amdgcn_global_load_lds((const unsigned*)(_gb + _vo), (LAS unsigned*)(lds + (bufoff) + ldsw + _i * 8192), 16, 0, 0); } } while (0)
; #define PG8_LDA(dst, b, h) do { _Pragma("unroll") for (int m = 0; m < 4; ++m) _Pragma("unroll") for (int k = 0; k < 2; ++k) dst[m][k] = *(const LAS bf16x8*)(lds + PG8_SA(b, h) + aoff + m * 2048 + k * 1024); } while (0)
; #define PG8_LDB(dst, b, h) do { _Pragma("unroll") for (int n = 0; n < 2; ++n) _Pragma("unroll") for (int k = 0; k < 2; ++k) dst[n][k] = *(const LAS bf16x8*)(lds + PG8_SB(b, h) + boff + n * 2048 + k * 1024); } while (0)
; #define PG8_MMA(ai, bj, At, Bt) do { __builtin_amdgcn_s_setprio(1); _Pragma("unroll") for (int m = 0; m < 4; ++m) _Pragma("unroll") for (int n = 0; n < 2; ++n) _Pragma("unroll") for (int k = 0; k < 2; ++k) \
;         acc[ai][bj][m][n] = __builtin_amdgcn_mfma_f32_16x16x32_bf16(Bt[n][k], At[m][k], acc[ai][bj][m][n], 0, 0, 0); __builtin_amdgcn_s_setprio(0); } while (0)
; #define PG8_WAIT_V(n) asm volatile("s_waitcnt vmcnt(" #n ")" ::: "memory")
; #define PG8_WAIT_L(n) asm volatile("s_waitcnt lgkmcnt(" #n ")" ::: "memory")
; #define PG8_BAR __builtin_amdgcn_s_barrier()
; #define PG8_SCHED __builtin_amdgcn_sched_barrier(0)
; template <class Epi, class Sched>
; DI void gemm_phase(int wv, LAS unsigned char* lds, const Gemm g, const Sched& S, const Epi& E) {
;     ...
;         for (int t = 0; t < nt; t += 2) {
;             const bool last = (t == nt - 2);
;             const char* a1 = cA + (size_t)(t + 1) * kstep;
;             const char* a2 = last ? nA : cA + (size_t)(t + 2) * kstep; const char* b2 = last ? nB : cB + (size_t)(t + 2) * kstep;
;             const char* a3 = a2 + kstep; const char* b3 = b2 + kstep;
;             PG8_LDB(B0, 0, 0); PG8_LDB(B1, 0, 1); PG8_SCHED; PG8_LDA(At, 0, 0); PG8_STAGE(PG8_SA(1, 1), a1 + hstepA, voffA);
;     ...
;             PG8_LDA(At, 1, 1); PG8_STAGE(PG8_SB(1, 0), b3, voffB); PG8_STAGE(PG8_SB(1, 1), b3 + hstepB, voffB); PG8_STAGE(PG8_SA(1, 0), a3, voffA);
;             PG8_WAIT_V(8); PG8_WAIT_L(0); PG8_BAR; PG8_MMA(1, 0, At, B0); PG8_MMA(1, 1, At, B1); PG8_BAR; PG8_SCHED;
	s_add_u32 s30, s28, 0x80
	s_addc_u32 s31, s29, 0
	v_mov_b32_e32 v177, v171
	s_add_i32 s61, s61, s38
	s_mov_b32 m0, s61
	s_nop 0
	global_load_lds_dwordx4 v177, s[30:31]
	v_mov_b32_e32 v177, v173
	s_add_i32 m0, s61, 0x2000
	s_add_u32 s28, s28, 0x40080
	global_load_lds_dwordx4 v177, s[30:31]
	s_addc_u32 s29, s29, 0
	v_mov_b32_e32 v177, v171
	s_add_i32 s30, s64, s38
	s_mov_b32 m0, s30
	s_nop 0
	global_load_lds_dwordx4 v177, s[28:29]
	v_mov_b32_e32 v177, v173
	s_add_i32 m0, s30, 0x2000
	s_nop 0
	global_load_lds_dwordx4 v177, s[28:29]
	v_mov_b32_e32 v177, v170
	s_mov_b32 m0, s50
	s_nop 0
	global_load_lds_dwordx4 v177, s[26:27]
	v_mov_b32_e32 v177, v172
	s_mov_b32 m0, s51
	s_nop 0
	global_load_lds_dwordx4 v177, s[26:27]
	ds_read_b128 v[162:165], v176 offset:49152
	ds_read_b128 v[166:169], v176 offset:50176
	ds_read_b128 v[178:181], v176 offset:51200
	ds_read_b128 v[182:185], v176 offset:52224
	ds_read_b128 v[186:189], v176 offset:53248
	ds_read_b128 v[190:193], v176 offset:54272
	ds_read_b128 v[194:197], v176 offset:55296
	ds_read_b128 v[198:201], v176 offset:56320
	s_waitcnt vmcnt(8)
	s_waitcnt lgkmcnt(0)
	s_barrier
	s_setprio 1
	s_waitcnt lgkmcnt(0)
	v_mfma_f32_16x16x32_bf16 v[62:65], v[98:101], v[162:165], v[62:65]
	v_mfma_f32_16x16x32_bf16 v[58:61], v[138:141], v[162:165], v[58:61]
	v_mfma_f32_16x16x32_bf16 v[46:49], v[98:101], v[178:181], v[46:49]
	v_mfma_f32_16x16x32_bf16 v[42:45], v[138:141], v[178:181], v[42:45]
	v_mfma_f32_16x16x32_bf16 v[30:33], v[98:101], v[186:189], v[30:33]
	v_mfma_f32_16x16x32_bf16 v[26:29], v[138:141], v[186:189], v[26:29]
	v_mfma_f32_16x16x32_bf16 v[14:17], v[98:101], v[194:197], v[14:17]
	v_mfma_f32_16x16x32_bf16 v[10:13], v[138:141], v[194:197], v[10:13]
	v_mfma_f32_16x16x32_bf16 v[62:65], v[118:121], v[166:169], v[62:65]
	v_mfma_f32_16x16x32_bf16 v[58:61], v[142:145], v[166:169], v[58:61]
	v_mfma_f32_16x16x32_bf16 v[46:49], v[118:121], v[182:185], v[46:49]
	v_mfma_f32_16x16x32_bf16 v[42:45], v[142:145], v[182:185], v[42:45]
	v_mfma_f32_16x16x32_bf16 v[30:33], v[118:121], v[190:193], v[30:33]
	v_mfma_f32_16x16x32_bf16 v[26:29], v[142:145], v[190:193], v[26:29]
	v_mfma_f32_16x16x32_bf16 v[14:17], v[118:121], v[198:201], v[14:17]
	v_mfma_f32_16x16x32_bf16 v[10:13], v[142:145], v[198:201], v[10:13]
	s_setprio 0
	s_setprio 1
	v_mfma_f32_16x16x32_bf16 v[54:57], v[146:149], v[162:165], v[54:57]
	v_mfma_f32_16x16x32_bf16 v[50:53], v[154:157], v[162:165], v[50:53]
	v_mfma_f32_16x16x32_bf16 v[38:41], v[146:149], v[178:181], v[38:41]
	v_mfma_f32_16x16x32_bf16 v[34:37], v[154:157], v[178:181], v[34:37]
	v_mfma_f32_16x16x32_bf16 v[22:25], v[146:149], v[186:189], v[22:25]
	v_mfma_f32_16x16x32_bf16 v[18:21], v[154:157], v[186:189], v[18:21]
	v_mfma_f32_16x16x32_bf16 v[6:9], v[146:149], v[194:197], v[6:9]
	v_mfma_f32_16x16x32_bf16 v[2:5], v[154:157], v[194:197], v[2:5]
	v_mfma_f32_16x16x32_bf16 v[54:57], v[150:153], v[166:169], v[54:57]
	v_mfma_f32_16x16x32_bf16 v[50:53], v[158:161], v[166:169], v[50:53]
	v_mfma_f32_16x16x32_bf16 v[38:41], v[150:153], v[182:185], v[38:41]
	v_mfma_f32_16x16x32_bf16 v[34:37], v[158:161], v[182:185], v[34:37]
	v_mfma_f32_16x16x32_bf16 v[22:25], v[150:153], v[190:193], v[22:25]
	v_mfma_f32_16x16x32_bf16 v[18:21], v[158:161], v[190:193], v[18:21]
	v_mfma_f32_16x16x32_bf16 v[6:9], v[150:153], v[198:201], v[6:9]
	v_mfma_f32_16x16x32_bf16 v[2:5], v[158:161], v[198:201], v[2:5]
	s_setprio 0
	s_barrier
	s_add_i32 s60, s60, 2
	s_add_u32 s56, s56, 0x100
	s_addc_u32 s57, s57, 0
	s_add_u32 s2, s2, 0x100
	s_addc_u32 s3, s3, 0
	s_cmp_gt_u32 s60, 13
.LBB0_1817:
	s_add_u32 s26, s2, 0xfffc0080
	s_addc_u32 s27, s3, -1
	s_cmp_eq_u32 s60, 12
	s_cselect_b32 s30, s23, s26
	s_cselect_b32 s31, s1, s27
	s_cselect_b32 s28, s55, s56
	s_cselect_b32 s29, s17, s57
	s_add_u32 s26, s30, 0x80
	s_addc_u32 s27, s31, 0
	s_add_i32 s61, 0, 0x10000
	s_add_i32 s66, 0, 0x14000
	s_mov_b64 s[64:65], s[2:3]
	v_mov_b32_e32 v177, v170
	s_add_i32 m0, s46, 0xc000
	s_nop 0
	global_load_lds_dwordx4 v177, s[64:65]
	v_mov_b32_e32 v177, v172
	s_add_i32 m0, s46, 0xe000
	s_nop 0
	global_load_lds_dwordx4 v177, s[64:65]
	v_add_u32_e32 v142, s61, v0
	v_add_u32_e32 v158, s66, v0
	ds_read_b128 v[98:101], v142
	ds_read_b128 v[118:121], v142 offset:1024
	ds_read_b128 v[138:141], v142 offset:2048
	ds_read_b128 v[142:145], v142 offset:3072
	ds_read_b128 v[146:149], v158
	ds_read_b128 v[150:153], v158 offset:1024
	ds_read_b128 v[154:157], v158 offset:2048
	ds_read_b128 v[158:161], v158 offset:3072
	ds_read_b128 v[162:165], v176
	ds_read_b128 v[166:169], v176 offset:1024
	ds_read_b128 v[178:181], v176 offset:2048
	ds_read_b128 v[182:185], v176 offset:3072
	ds_read_b128 v[186:189], v176 offset:4096
	ds_read_b128 v[190:193], v176 offset:5120
	ds_read_b128 v[194:197], v176 offset:6144
	ds_read_b128 v[198:201], v176 offset:7168
	s_waitcnt vmcnt(8)
	s_waitcnt lgkmcnt(0)
	s_barrier
; #define PG8_STAGE(bufoff, gbase, voff) do { const char* _gb = (const char*)(gbase); asm volatile("" : "+s"(_gb)); _Pragma("unroll") for (int _i = 0; _i < 2; ++_i) { \
;         unsigned _vo = (voff)[_i]; asm volatile("" : "+v"(_vo));     \
;         __builtin_amdgcn_global_load_lds((const unsigned*)(_gb + _vo), (LAS unsigned*)(lds + (bufoff) + ldsw + _i * 8192), 16, 0, 0); } } while (0)
; #define PG8_LDA(dst, b, h) do { _Pragma("unroll") for (int m = 0; m < 4; ++m) _Pragma("unroll") for (int k = 0; k < 2; ++k) dst[m][k] = *(const LAS bf16x8*)(lds + PG8_SA(b, h) + aoff + m * 2048 + k * 1024); } while (0)
; #define PG8_MMA(ai, bj, At, Bt) do { __builtin_amdgcn_s_setprio(1); _Pragma("unroll") for (int m = 0; m < 4; ++m) _Pragma("unroll") for (int n = 0; n < 2; ++n) _Pragma("unroll") for (int k = 0; k < 2; ++k) \
;         acc[ai][bj][m][n] = __builtin_amdgcn_mfma_f32_16x16x32_bf16(Bt[n][k], At[m][k], acc[ai][bj][m][n], 0, 0, 0); __builtin_amdgcn_s_setprio(0); } while (0)
; #define PG8_WAIT_V(n) asm volatile("s_waitcnt vmcnt(" #n ")" ::: "memory")
; #define PG8_WAIT_L(n) asm volatile("s_waitcnt lgkmcnt(" #n ")" ::: "memory")
; #define PG8_BAR __builtin_amdgcn_s_barrier()
; #define PG8_SCHED __builtin_amdgcn_sched_barrier(0)
; template <class Epi, class Sched>
; DI void gemm_phase(int wv, LAS unsigned char* lds, const Gemm g, const Sched& S, const Epi& E) {
;     ...
;             PG8_WAIT_V(8); PG8_WAIT_L(0); PG8_BAR; PG8_MMA(0, 0, At, B0); PG8_MMA(0, 1, At, B1); PG8_BAR; PG8_SCHED;
;             PG8_LDA(At, 0, 1); PG8_STAGE(PG8_SB(0, 0), b2, voffB); PG8_STAGE(PG8_SB(0, 1), b2 + hstepB, voffB); PG8_STAGE(PG8_SA(0, 0), a2, voffA);
;             PG8_WAIT_V(8); PG8_WAIT_L(0); PG8_BAR; PG8_MMA(1, 0, At, B0); PG8_MMA(1, 1, At, B1); PG8_BAR; PG8_SCHED;
	s_setprio 1
	s_waitcnt lgkmcnt(0)
	v_mfma_f32_16x16x32_bf16 v[134:137], v[98:101], v[162:165], v[134:137]
	v_mfma_f32_16x16x32_bf16 v[130:133], v[138:141], v[162:165], v[130:133]
	v_mfma_f32_16x16x32_bf16 v[114:117], v[98:101], v[178:181], v[114:117]
	v_mfma_f32_16x16x32_bf16 v[110:113], v[138:141], v[178:181], v[110:113]
	v_mfma_f32_16x16x32_bf16 v[94:97], v[98:101], v[186:189], v[94:97]
	v_mfma_f32_16x16x32_bf16 v[90:93], v[138:141], v[186:189], v[90:93]
	v_mfma_f32_16x16x32_bf16 v[78:81], v[98:101], v[194:197], v[78:81]
	v_mfma_f32_16x16x32_bf16 v[74:77], v[138:141], v[194:197], v[74:77]
	v_mfma_f32_16x16x32_bf16 v[134:137], v[118:121], v[166:169], v[134:137]
	v_mfma_f32_16x16x32_bf16 v[130:133], v[142:145], v[166:169], v[130:133]
	v_mfma_f32_16x16x32_bf16 v[114:117], v[118:121], v[182:185], v[114:117]
	v_mfma_f32_16x16x32_bf16 v[110:113], v[142:145], v[182:185], v[110:113]
	v_mfma_f32_16x16x32_bf16 v[94:97], v[118:121], v[190:193], v[94:97]
	v_mfma_f32_16x16x32_bf16 v[90:93], v[142:145], v[190:193], v[90:93]
	v_mfma_f32_16x16x32_bf16 v[78:81], v[118:121], v[198:201], v[78:81]
	v_mfma_f32_16x16x32_bf16 v[74:77], v[142:145], v[198:201], v[74:77]
	s_setprio 0
	s_setprio 1
	v_mfma_f32_16x16x32_bf16 v[126:129], v[146:149], v[162:165], v[126:129]
	v_mfma_f32_16x16x32_bf16 v[122:125], v[154:157], v[162:165], v[122:125]
	v_mfma_f32_16x16x32_bf16 v[106:109], v[146:149], v[178:181], v[106:109]
	v_mfma_f32_16x16x32_bf16 v[102:105], v[154:157], v[178:181], v[102:105]
	v_mfma_f32_16x16x32_bf16 v[86:89], v[146:149], v[186:189], v[86:89]
	v_mfma_f32_16x16x32_bf16 v[82:85], v[154:157], v[186:189], v[82:85]
	v_mfma_f32_16x16x32_bf16 v[70:73], v[146:149], v[194:197], v[70:73]
	v_mfma_f32_16x16x32_bf16 v[66:69], v[154:157], v[194:197], v[66:69]
	v_mfma_f32_16x16x32_bf16 v[126:129], v[150:153], v[166:169], v[126:129]
	v_mfma_f32_16x16x32_bf16 v[122:125], v[158:161], v[166:169], v[122:125]
	v_mfma_f32_16x16x32_bf16 v[106:109], v[150:153], v[182:185], v[106:109]
	v_mfma_f32_16x16x32_bf16 v[102:105], v[158:161], v[182:185], v[102:105]
	v_mfma_f32_16x16x32_bf16 v[86:89], v[150:153], v[190:193], v[86:89]
	v_mfma_f32_16x16x32_bf16 v[82:85], v[158:161], v[190:193], v[82:85]
	v_mfma_f32_16x16x32_bf16 v[70:73], v[150:153], v[198:201], v[70:73]
	v_mfma_f32_16x16x32_bf16 v[66:69], v[158:161], v[198:201], v[66:69]
	s_setprio 0
	s_barrier
	s_mov_b64 s[64:65], s[28:29]
	v_mov_b32_e32 v177, v171
	s_add_i32 s61, s61, s38
	s_mov_b32 m0, s61
	s_nop 0
	global_load_lds_dwordx4 v177, s[64:65]
	v_mov_b32_e32 v177, v173
	s_add_i32 m0, s61, 0x2000
	s_nop 0
	global_load_lds_dwordx4 v177, s[64:65]
	s_add_u32 s64, s28, 0x40000
	s_addc_u32 s65, s29, 0
	v_mov_b32_e32 v177, v171
	s_add_i32 s61, s66, s38
	s_mov_b32 m0, s61
	s_nop 0
	global_load_lds_dwordx4 v177, s[64:65]
	v_mov_b32_e32 v177, v173
	s_add_i32 m0, s61, 0x2000
	s_nop 0
	global_load_lds_dwordx4 v177, s[64:65]
	s_mov_b64 s[64:65], s[30:31]
	v_mov_b32_e32 v177, v170
	s_mov_b32 m0, s46
	s_nop 0
	global_load_lds_dwordx4 v177, s[64:65]
	v_mov_b32_e32 v177, v172
	s_mov_b32 m0, s47
	s_nop 0
	global_load_lds_dwordx4 v177, s[64:65]
	ds_read_b128 v[162:165], v176 offset:16384
	ds_read_b128 v[166:169], v176 offset:17408
	ds_read_b128 v[178:181], v176 offset:18432
	ds_read_b128 v[182:185], v176 offset:19456
	ds_read_b128 v[186:189], v176 offset:20480
	ds_read_b128 v[190:193], v176 offset:21504
	ds_read_b128 v[194:197], v176 offset:22528
	ds_read_b128 v[198:201], v176 offset:23552
	s_waitcnt vmcnt(8)
	s_waitcnt lgkmcnt(0)
	s_barrier
	s_setprio 1
	s_waitcnt lgkmcnt(0)
	v_mfma_f32_16x16x32_bf16 v[62:65], v[98:101], v[162:165], v[62:65]
	v_mfma_f32_16x16x32_bf16 v[58:61], v[138:141], v[162:165], v[58:61]
	v_mfma_f32_16x16x32_bf16 v[46:49], v[98:101], v[178:181], v[46:49]
	v_mfma_f32_16x16x32_bf16 v[42:45], v[138:141], v[178:181], v[42:45]
	v_mfma_f32_16x16x32_bf16 v[30:33], v[98:101], v[186:189], v[30:33]
	v_mfma_f32_16x16x32_bf16 v[26:29], v[138:141], v[186:189], v[26:29]
	v_mfma_f32_16x16x32_bf16 v[14:17], v[98:101], v[194:197], v[14:17]
	v_mfma_f32_16x16x32_bf16 v[10:13], v[138:141], v[194:197], v[10:13]
	v_mfma_f32_16x16x32_bf16 v[62:65], v[118:121], v[166:169], v[62:65]
	v_mfma_f32_16x16x32_bf16 v[58:61], v[142:145], v[166:169], v[58:61]
	v_mfma_f32_16x16x32_bf16 v[46:49], v[118:121], v[182:185], v[46:49]
	v_mfma_f32_16x16x32_bf16 v[42:45], v[142:145], v[182:185], v[42:45]
	v_mfma_f32_16x16x32_bf16 v[30:33], v[118:121], v[190:193], v[30:33]
	v_mfma_f32_16x16x32_bf16 v[26:29], v[142:145], v[190:193], v[26:29]
	v_mfma_f32_16x16x32_bf16 v[14:17], v[118:121], v[198:201], v[14:17]
	v_mfma_f32_16x16x32_bf16 v[10:13], v[142:145], v[198:201], v[10:13]
	s_setprio 0
	s_setprio 1
	v_mfma_f32_16x16x32_bf16 v[54:57], v[146:149], v[162:165], v[54:57]
	v_mfma_f32_16x16x32_bf16 v[50:53], v[154:157], v[162:165], v[50:53]
	v_mfma_f32_16x16x32_bf16 v[38:41], v[146:149], v[178:181], v[38:41]
	v_mfma_f32_16x16x32_bf16 v[34:37], v[154:157], v[178:181], v[34:37]
	v_mfma_f32_16x16x32_bf16 v[22:25], v[146:149], v[186:189], v[22:25]
	v_mfma_f32_16x16x32_bf16 v[18:21], v[154:157], v[186:189], v[18:21]
	v_mfma_f32_16x16x32_bf16 v[6:9], v[146:149], v[194:197], v[6:9]
	v_mfma_f32_16x16x32_bf16 v[2:5], v[154:157], v[194:197], v[2:5]
	v_mfma_f32_16x16x32_bf16 v[54:57], v[150:153], v[166:169], v[54:57]
	v_mfma_f32_16x16x32_bf16 v[50:53], v[158:161], v[166:169], v[50:53]
	v_mfma_f32_16x16x32_bf16 v[38:41], v[150:153], v[182:185], v[38:41]
	v_mfma_f32_16x16x32_bf16 v[34:37], v[158:161], v[182:185], v[34:37]
	v_mfma_f32_16x16x32_bf16 v[22:25], v[150:153], v[190:193], v[22:25]
	v_mfma_f32_16x16x32_bf16 v[18:21], v[158:161], v[190:193], v[18:21]
	v_mfma_f32_16x16x32_bf16 v[6:9], v[150:153], v[198:201], v[6:9]
	v_mfma_f32_16x16x32_bf16 v[2:5], v[158:161], v[198:201], v[2:5]
	s_setprio 0
	s_barrier
; #define PG8_STAGE(bufoff, gbase, voff) do { const char* _gb = (const char*)(gbase); asm volatile("" : "+s"(_gb)); _Pragma("unroll") for (int _i = 0; _i < 2; ++_i) { \
;         unsigned _vo = (voff)[_i]; asm volatile("" : "+v"(_vo));     \
;         __builtin_amdgcn_global_load_lds((const unsigned*)(_gb + _vo), (LAS unsigned*)(lds + (bufoff) + ldsw + _i * 8192), 16, 0, 0); } } while (0)
; #define PG8_LDA(dst, b, h) do { _Pragma("unroll") for (int m = 0; m < 4; ++m) _Pragma("unroll") for (int k = 0; k < 2; ++k) dst[m][k] = *(const LAS bf16x8*)(lds + PG8_SA(b, h) + aoff + m * 2048 + k * 1024); } while (0)
; #define PG8_LDB(dst, b, h) do { _Pragma("unroll") for (int n = 0; n < 2; ++n) _Pragma("unroll") for (int k = 0; k < 2; ++k) dst[n][k] = *(const LAS bf16x8*)(lds + PG8_SB(b, h) + boff + n * 2048 + k * 1024); } while (0)
; #define PG8_MMA(ai, bj, At, Bt) do { __builtin_amdgcn_s_setprio(1); _Pragma("unroll") for (int m = 0; m < 4; ++m) _Pragma("unroll") for (int n = 0; n < 2; ++n) _Pragma("unroll") for (int k = 0; k < 2; ++k) \
;         acc[ai][bj][m][n] = __builtin_amdgcn_mfma_f32_16x16x32_bf16(Bt[n][k], At[m][k], acc[ai][bj][m][n], 0, 0, 0); __builtin_amdgcn_s_setprio(0); } while (0)
; #define PG8_WAIT_V(n) asm volatile("s_waitcnt vmcnt(" #n ")" ::: "memory")
; #define PG8_WAIT_L(n) asm volatile("s_waitcnt lgkmcnt(" #n ")" ::: "memory")
; #define PG8_BAR __builtin_amdgcn_s_barrier()
; #define PG8_SCHED __builtin_amdgcn_sched_barrier(0)
; template <class Epi, class Sched>
; DI void gemm_phase(int wv, LAS unsigned char* lds, const Gemm g, const Sched& S, const Epi& E) {
;     ...
;             PG8_LDB(B0, 1, 0); PG8_LDB(B1, 1, 1); PG8_SCHED; PG8_LDA(At, 1, 0); PG8_STAGE(PG8_SA(0, 1), a2 + hstepA, voffA);
;             PG8_WAIT_V(8); PG8_WAIT_L(0); PG8_BAR; PG8_MMA(0, 0, At, B0); PG8_MMA(0, 1, At, B1); PG8_BAR; PG8_SCHED;
	s_add_i32 s61, 0, 0x18000
	s_add_i32 s64, 0, 0x1c000
	s_add_u32 s30, s30, 0x40000
	s_addc_u32 s31, s31, 0
	v_mov_b32_e32 v177, v170
	s_mov_b32 m0, s48
	s_nop 0
	global_load_lds_dwordx4 v177, s[30:31]
	v_mov_b32_e32 v177, v172
	s_mov_b32 m0, s49
	s_nop 0
	global_load_lds_dwordx4 v177, s[30:31]
	v_add_u32_e32 v142, s61, v0
	v_add_u32_e32 v158, s64, v0
	ds_read_b128 v[98:101], v142
	ds_read_b128 v[118:121], v142 offset:1024
	ds_read_b128 v[138:141], v142 offset:2048
	ds_read_b128 v[142:145], v142 offset:3072
	ds_read_b128 v[146:149], v158
	ds_read_b128 v[150:153], v158 offset:1024
	ds_read_b128 v[154:157], v158 offset:2048
	ds_read_b128 v[158:161], v158 offset:3072
	ds_read_b128 v[162:165], v176 offset:32768
	ds_read_b128 v[166:169], v176 offset:33792
	ds_read_b128 v[178:181], v176 offset:34816
	ds_read_b128 v[182:185], v176 offset:35840
	ds_read_b128 v[186:189], v176 offset:36864
	ds_read_b128 v[190:193], v176 offset:37888
	ds_read_b128 v[194:197], v176 offset:38912
	ds_read_b128 v[198:201], v176 offset:39936
	s_waitcnt vmcnt(8)
	s_waitcnt lgkmcnt(0)
	s_barrier
	s_setprio 1
	s_waitcnt lgkmcnt(0)
	v_mfma_f32_16x16x32_bf16 v[134:137], v[98:101], v[162:165], v[134:137]
	v_mfma_f32_16x16x32_bf16 v[130:133], v[138:141], v[162:165], v[130:133]
	v_mfma_f32_16x16x32_bf16 v[114:117], v[98:101], v[178:181], v[114:117]
	v_mfma_f32_16x16x32_bf16 v[110:113], v[138:141], v[178:181], v[110:113]
	v_mfma_f32_16x16x32_bf16 v[94:97], v[98:101], v[186:189], v[94:97]
	v_mfma_f32_16x16x32_bf16 v[90:93], v[138:141], v[186:189], v[90:93]
	v_mfma_f32_16x16x32_bf16 v[78:81], v[98:101], v[194:197], v[78:81]
	v_mfma_f32_16x16x32_bf16 v[74:77], v[138:141], v[194:197], v[74:77]
	v_mfma_f32_16x16x32_bf16 v[134:137], v[118:121], v[166:169], v[134:137]
	v_mfma_f32_16x16x32_bf16 v[130:133], v[142:145], v[166:169], v[130:133]
	v_mfma_f32_16x16x32_bf16 v[114:117], v[118:121], v[182:185], v[114:117]
	v_mfma_f32_16x16x32_bf16 v[110:113], v[142:145], v[182:185], v[110:113]
	v_mfma_f32_16x16x32_bf16 v[94:97], v[118:121], v[190:193], v[94:97]
	v_mfma_f32_16x16x32_bf16 v[90:93], v[142:145], v[190:193], v[90:93]
	v_mfma_f32_16x16x32_bf16 v[78:81], v[118:121], v[198:201], v[78:81]
	v_mfma_f32_16x16x32_bf16 v[74:77], v[142:145], v[198:201], v[74:77]
	s_setprio 0
	s_setprio 1
	v_mfma_f32_16x16x32_bf16 v[126:129], v[146:149], v[162:165], v[126:129]
	v_mfma_f32_16x16x32_bf16 v[122:125], v[154:157], v[162:165], v[122:125]
	v_mfma_f32_16x16x32_bf16 v[106:109], v[146:149], v[178:181], v[106:109]
	v_mfma_f32_16x16x32_bf16 v[102:105], v[154:157], v[178:181], v[102:105]
	v_mfma_f32_16x16x32_bf16 v[86:89], v[146:149], v[186:189], v[86:89]
	v_mfma_f32_16x16x32_bf16 v[82:85], v[154:157], v[186:189], v[82:85]
	v_mfma_f32_16x16x32_bf16 v[70:73], v[146:149], v[194:197], v[70:73]
	v_mfma_f32_16x16x32_bf16 v[66:69], v[154:157], v[194:197], v[66:69]
	v_mfma_f32_16x16x32_bf16 v[126:129], v[150:153], v[166:169], v[126:129]
	v_mfma_f32_16x16x32_bf16 v[122:125], v[158:161], v[166:169], v[122:125]
	v_mfma_f32_16x16x32_bf16 v[106:109], v[150:153], v[182:185], v[106:109]
	v_mfma_f32_16x16x32_bf16 v[102:105], v[158:161], v[182:185], v[102:105]
	v_mfma_f32_16x16x32_bf16 v[86:89], v[150:153], v[190:193], v[86:89]
	v_mfma_f32_16x16x32_bf16 v[82:85], v[158:161], v[190:193], v[82:85]
	v_mfma_f32_16x16x32_bf16 v[70:73], v[150:153], v[198:201], v[70:73]
	v_mfma_f32_16x16x32_bf16 v[66:69], v[158:161], v[198:201], v[66:69]
	s_setprio 0
	s_barrier
; #define PG8_STAGE(bufoff, gbase, voff) do { const char* _gb = (const char*)(gbase); asm volatile("" : "+s"(_gb)); _Pragma("unroll") for (int _i = 0; _i < 2; ++_i) { \
;         unsigned _vo = (voff)[_i]; asm volatile("" : "+v"(_vo));     \
;         __builtin_amdgcn_global_load_lds((const unsigned*)(_gb + _vo), (LAS unsigned*)(lds + (bufoff) + ldsw + _i * 8192), 16, 0, 0); } } while (0)
; #define PG8_LDA(dst, b, h) do { _Pragma("unroll") for (int m = 0; m < 4; ++m) _Pragma("unroll") for (int k = 0; k < 2; ++k) dst[m][k] = *(const LAS bf16x8*)(lds + PG8_SA(b, h) + aoff + m * 2048 + k * 1024); } while (0)
; #define PG8_MMA(ai, bj, At, Bt) do { __builtin_amdgcn_s_setprio(1); _Pragma("unroll") for (int m = 0; m < 4; ++m) _Pragma("unroll") for (int n = 0; n < 2; ++n) _Pragma("unroll") for (int k = 0; k < 2; ++k) \
;         acc[ai][bj][m][n] = __builtin_amdgcn_mfma_f32_16x16x32_bf16(Bt[n][k], At[m][k], acc[ai][bj][m][n], 0, 0, 0); __builtin_amdgcn_s_setprio(0); } while (0)
; #define PG8_WAIT_V(n) asm volatile("s_waitcnt vmcnt(" #n ")" ::: "memory")
; #define PG8_WAIT_L(n) asm volatile("s_waitcnt lgkmcnt(" #n ")" ::: "memory")
; #define PG8_BAR __builtin_amdgcn_s_barrier()
; #define PG8_SCHED __builtin_amdgcn_sched_barrier(0)
; template <class Epi, class Sched>
; DI void gemm_phase(int wv, LAS unsigned char* lds, const Gemm g, const Sched& S, const Epi& E) {
;     ...
;             PG8_LDA(At, 1, 1); PG8_STAGE(PG8_SB(1, 0), b3, voffB); PG8_STAGE(PG8_SB(1, 1), b3 + hstepB, voffB); PG8_STAGE(PG8_SA(1, 0), a3, voffA);
;             PG8_WAIT_V(8); PG8_WAIT_L(0); PG8_BAR; PG8_MMA(1, 0, At, B0); PG8_MMA(1, 1, At, B1); PG8_BAR; PG8_SCHED;
;         }
;         PG8_SCHED;
;         if (wr == 0) PG8_BAR;
	s_add_u32 s30, s28, 0x80
	s_addc_u32 s31, s29, 0
	v_mov_b32_e32 v177, v171
	s_add_i32 s61, s61, s38
	s_mov_b32 m0, s61
	s_nop 0
	global_load_lds_dwordx4 v177, s[30:31]
	v_mov_b32_e32 v177, v173
	s_add_i32 m0, s61, 0x2000
	s_add_u32 s28, s28, 0x40080
	global_load_lds_dwordx4 v177, s[30:31]
	s_addc_u32 s29, s29, 0
	v_mov_b32_e32 v177, v171
	s_add_i32 s30, s64, s38
	s_mov_b32 m0, s30
	s_nop 0
	global_load_lds_dwordx4 v177, s[28:29]
	v_mov_b32_e32 v177, v173
	s_add_i32 m0, s30, 0x2000
	s_nop 0
	global_load_lds_dwordx4 v177, s[28:29]
	v_mov_b32_e32 v177, v170
	s_mov_b32 m0, s50
	s_nop 0
	global_load_lds_dwordx4 v177, s[26:27]
	v_mov_b32_e32 v177, v172
	s_mov_b32 m0, s51
	s_nop 0
	global_load_lds_dwordx4 v177, s[26:27]
	ds_read_b128 v[162:165], v176 offset:49152
	ds_read_b128 v[166:169], v176 offset:50176
	ds_read_b128 v[178:181], v176 offset:51200
	ds_read_b128 v[182:185], v176 offset:52224
	ds_read_b128 v[186:189], v176 offset:53248
	ds_read_b128 v[190:193], v176 offset:54272
	ds_read_b128 v[194:197], v176 offset:55296
	ds_read_b128 v[198:201], v176 offset:56320
	s_waitcnt vmcnt(8)
	s_waitcnt lgkmcnt(0)
	s_barrier
	s_setprio 1
	s_waitcnt lgkmcnt(0)
	v_mfma_f32_16x16x32_bf16 v[62:65], v[98:101], v[162:165], v[62:65]
	v_mfma_f32_16x16x32_bf16 v[58:61], v[138:141], v[162:165], v[58:61]
	v_mfma_f32_16x16x32_bf16 v[46:49], v[98:101], v[178:181], v[46:49]
	v_mfma_f32_16x16x32_bf16 v[42:45], v[138:141], v[178:181], v[42:45]
	v_mfma_f32_16x16x32_bf16 v[30:33], v[98:101], v[186:189], v[30:33]
	v_mfma_f32_16x16x32_bf16 v[26:29], v[138:141], v[186:189], v[26:29]
	v_mfma_f32_16x16x32_bf16 v[14:17], v[98:101], v[194:197], v[14:17]
	v_mfma_f32_16x16x32_bf16 v[10:13], v[138:141], v[194:197], v[10:13]
	v_mfma_f32_16x16x32_bf16 v[62:65], v[118:121], v[166:169], v[62:65]
	v_mfma_f32_16x16x32_bf16 v[58:61], v[142:145], v[166:169], v[58:61]
	v_mfma_f32_16x16x32_bf16 v[46:49], v[118:121], v[182:185], v[46:49]
	v_mfma_f32_16x16x32_bf16 v[42:45], v[142:145], v[182:185], v[42:45]
	v_mfma_f32_16x16x32_bf16 v[30:33], v[118:121], v[190:193], v[30:33]
	v_mfma_f32_16x16x32_bf16 v[26:29], v[142:145], v[190:193], v[26:29]
	v_mfma_f32_16x16x32_bf16 v[14:17], v[118:121], v[198:201], v[14:17]
	v_mfma_f32_16x16x32_bf16 v[10:13], v[142:145], v[198:201], v[10:13]
	s_setprio 0
	s_setprio 1
	v_mfma_f32_16x16x32_bf16 v[54:57], v[146:149], v[162:165], v[54:57]
	v_mfma_f32_16x16x32_bf16 v[50:53], v[154:157], v[162:165], v[50:53]
	v_mfma_f32_16x16x32_bf16 v[38:41], v[146:149], v[178:181], v[38:41]
	v_mfma_f32_16x16x32_bf16 v[34:37], v[154:157], v[178:181], v[34:37]
	v_mfma_f32_16x16x32_bf16 v[22:25], v[146:149], v[186:189], v[22:25]
	v_mfma_f32_16x16x32_bf16 v[18:21], v[154:157], v[186:189], v[18:21]
	v_mfma_f32_16x16x32_bf16 v[6:9], v[146:149], v[194:197], v[6:9]
	v_mfma_f32_16x16x32_bf16 v[2:5], v[154:157], v[194:197], v[2:5]
	v_mfma_f32_16x16x32_bf16 v[54:57], v[150:153], v[166:169], v[54:57]
	v_mfma_f32_16x16x32_bf16 v[50:53], v[158:161], v[166:169], v[50:53]
	v_mfma_f32_16x16x32_bf16 v[38:41], v[150:153], v[182:185], v[38:41]
	v_mfma_f32_16x16x32_bf16 v[34:37], v[158:161], v[182:185], v[34:37]
	v_mfma_f32_16x16x32_bf16 v[22:25], v[150:153], v[190:193], v[22:25]
	v_mfma_f32_16x16x32_bf16 v[18:21], v[158:161], v[190:193], v[18:21]
	v_mfma_f32_16x16x32_bf16 v[6:9], v[150:153], v[198:201], v[6:9]
	v_mfma_f32_16x16x32_bf16 v[2:5], v[158:161], v[198:201], v[2:5]
	s_setprio 0
	s_barrier
	s_add_i32 s60, s60, 2
	s_add_u32 s56, s56, 0x100
	s_addc_u32 s57, s57, 0
	s_add_u32 s2, s2, 0x100
	s_addc_u32 s3, s3, 0
	s_cmp_gt_u32 s60, 13
	s_cbranch_scc0 .LBB0_1817
	s_and_b64 vcc, exec, s[12:13]
	s_cbranch_vccz .LBB0_1820
	s_barrier
